# P28: SGU tail u/g loads requested before the last MFMA batch and the barrier in front of the tail (counted waits +16)
# baseline (speedup 1.0000x reference)
.Lsgu_nogain:
	s_waitcnt lgkmcnt(0)
	s_barrier
	v_add_f32_e32 v78, v80, v81
	ds_bpermute_b32 v79, v198, v78
	v_lshl_add_u32 v80, v85, 2, 0
	v_add_u32_e32 v104, 0x11000, v80
	v_mul_lo_u32 v80, v84, s1
	v_add3_u32 v105, 0, v80, v0
	s_waitcnt lgkmcnt(0)
	v_add_f32_e32 v78, v78, v79
	v_fmamk_f32 v78, v78, 0x3b800000, v202
	v_mul_f32_e32 v79, 0x4b800000, v78
	v_cmp_gt_f32_e32 vcc, s47, v78
	v_and_b32_e32 v111, 31, v110
	s_movk_i32 s1, 0x6000
	v_cndmask_b32_e32 v78, v78, v79, vcc
	v_rsq_f32_e32 v90, v78
	ds_read_b128 v[78:81], v104
	ds_read_b128 v[82:85], v104 offset:16
	v_mul_f32_e32 v0, 0x45800000, v90
	v_cndmask_b32_e32 v0, v90, v0, vcc
	v_pk_mul_f32 v[90:91], v[102:103], v[0:1] op_sel_hi:[1,0]
	v_pk_mul_f32 v[88:89], v[88:89], v[0:1] op_sel_hi:[1,0]
	s_waitcnt lgkmcnt(1)
	v_pk_mul_f32 v[78:79], v[78:79], v[90:91]
	v_pk_mul_f32 v[90:91], v[92:93], v[0:1] op_sel_hi:[1,0]
	v_cvt_pk_bf16_f32 v78, v78, v79
	v_pk_mul_f32 v[80:81], v[80:81], v[90:91]
	v_pk_mul_f32 v[90:91], v[130:131], v[0:1] op_sel_hi:[1,0]
	v_cvt_pk_bf16_f32 v79, v80, v81
	v_pk_mul_f32 v[80:81], v[114:115], v[0:1] op_sel_hi:[1,0]
	v_pk_mul_f32 v[14:15], v[14:15], v[0:1] op_sel_hi:[1,0]
	s_waitcnt lgkmcnt(0)
	v_pk_mul_f32 v[80:81], v[82:83], v[80:81]
	v_pk_mul_f32 v[82:83], v[112:113], v[0:1] op_sel_hi:[1,0]
	v_cvt_pk_bf16_f32 v80, v80, v81
	v_pk_mul_f32 v[82:83], v[84:85], v[82:83]
	v_pk_mul_f32 v[12:13], v[12:13], v[0:1] op_sel_hi:[1,0]
	v_cvt_pk_bf16_f32 v81, v82, v83
	ds_write2_b64 v105, v[78:79], v[80:81] offset1:1
	ds_read_b128 v[78:81], v104 offset:32
	ds_read_b128 v[82:85], v104 offset:48
	v_pk_mul_f32 v[10:11], v[10:11], v[0:1] op_sel_hi:[1,0]
	v_pk_mul_f32 v[8:9], v[8:9], v[0:1] op_sel_hi:[1,0]
	v_pk_mul_f32 v[6:7], v[6:7], v[0:1] op_sel_hi:[1,0]
	s_waitcnt lgkmcnt(1)
	v_pk_mul_f32 v[78:79], v[78:79], v[90:91]
	v_pk_mul_f32 v[90:91], v[144:145], v[0:1] op_sel_hi:[1,0]
	v_cvt_pk_bf16_f32 v78, v78, v79
	v_pk_mul_f32 v[80:81], v[80:81], v[90:91]
	v_pk_mul_f32 v[90:91], v[176:177], v[0:1] op_sel_hi:[1,0]
	v_cvt_pk_bf16_f32 v79, v80, v81
	v_pk_mul_f32 v[80:81], v[142:143], v[0:1] op_sel_hi:[1,0]
	s_waitcnt lgkmcnt(0)
	v_pk_mul_f32 v[80:81], v[82:83], v[80:81]
	v_pk_mul_f32 v[82:83], v[154:155], v[0:1] op_sel_hi:[1,0]
	v_cvt_pk_bf16_f32 v80, v80, v81
	v_pk_mul_f32 v[82:83], v[84:85], v[82:83]
	s_nop 0
	v_cvt_pk_bf16_f32 v81, v82, v83
	ds_write2_b64 v105, v[78:79], v[80:81] offset0:2 offset1:3
	ds_read_b128 v[78:81], v104 offset:64
	ds_read_b128 v[82:85], v104 offset:80
	s_waitcnt lgkmcnt(1)
	v_pk_mul_f32 v[78:79], v[78:79], v[90:91]
	v_pk_mul_f32 v[90:91], v[96:97], v[0:1] op_sel_hi:[1,0]
	v_cvt_pk_bf16_f32 v78, v78, v79
	v_pk_mul_f32 v[80:81], v[80:81], v[90:91]
	v_pk_mul_f32 v[90:91], v[150:151], v[0:1] op_sel_hi:[1,0]
	v_cvt_pk_bf16_f32 v79, v80, v81
	v_pk_mul_f32 v[80:81], v[172:173], v[0:1] op_sel_hi:[1,0]
	s_waitcnt lgkmcnt(0)
	v_pk_mul_f32 v[80:81], v[82:83], v[80:81]
	v_pk_mul_f32 v[82:83], v[94:95], v[0:1] op_sel_hi:[1,0]
	v_cvt_pk_bf16_f32 v80, v80, v81
	v_pk_mul_f32 v[82:83], v[84:85], v[82:83]
	s_nop 0
	v_cvt_pk_bf16_f32 v81, v82, v83
	ds_write2_b64 v105, v[78:79], v[80:81] offset0:4 offset1:5
	ds_read_b128 v[78:81], v104 offset:96
	ds_read_b128 v[82:85], v104 offset:112
	s_waitcnt lgkmcnt(1)
	v_pk_mul_f32 v[78:79], v[78:79], v[90:91]
	v_pk_mul_f32 v[90:91], v[140:141], v[0:1] op_sel_hi:[1,0]
	v_cvt_pk_bf16_f32 v78, v78, v79
	v_pk_mul_f32 v[80:81], v[80:81], v[90:91]
	v_pk_mul_f32 v[90:91], v[118:119], v[0:1] op_sel_hi:[1,0]
	v_cvt_pk_bf16_f32 v79, v80, v81
	v_pk_mul_f32 v[80:81], v[100:101], v[0:1] op_sel_hi:[1,0]
	s_waitcnt lgkmcnt(0)
	v_pk_mul_f32 v[80:81], v[82:83], v[80:81]
	v_pk_mul_f32 v[82:83], v[98:99], v[0:1] op_sel_hi:[1,0]
	v_cvt_pk_bf16_f32 v80, v80, v81
	v_pk_mul_f32 v[82:83], v[84:85], v[82:83]
	s_nop 0
	v_cvt_pk_bf16_f32 v81, v82, v83
	ds_write2_b64 v105, v[78:79], v[80:81] offset0:6 offset1:7
	ds_read_b128 v[78:81], v104 offset:128
	ds_read_b128 v[82:85], v104 offset:144
	s_waitcnt lgkmcnt(1)
	v_pk_mul_f32 v[78:79], v[78:79], v[90:91]
	v_pk_mul_f32 v[90:91], v[162:163], v[0:1] op_sel_hi:[1,0]
	v_cvt_pk_bf16_f32 v78, v78, v79
	v_pk_mul_f32 v[80:81], v[80:81], v[90:91]
	v_pk_mul_f32 v[90:91], v[192:193], v[0:1] op_sel_hi:[1,0]
	v_cvt_pk_bf16_f32 v79, v80, v81
	v_pk_mul_f32 v[80:81], v[182:183], v[0:1] op_sel_hi:[1,0]
	s_waitcnt lgkmcnt(0)
	v_pk_mul_f32 v[80:81], v[82:83], v[80:81]
	v_pk_mul_f32 v[82:83], v[152:153], v[0:1] op_sel_hi:[1,0]
	v_cvt_pk_bf16_f32 v80, v80, v81
	v_pk_mul_f32 v[82:83], v[84:85], v[82:83]
	s_nop 0
	v_cvt_pk_bf16_f32 v81, v82, v83
	ds_write2_b64 v105, v[78:79], v[80:81] offset0:8 offset1:9
	ds_read_b128 v[78:81], v104 offset:160
	ds_read_b128 v[82:85], v104 offset:176
	s_waitcnt lgkmcnt(1)
	v_pk_mul_f32 v[78:79], v[78:79], v[90:91]
	v_pk_mul_f32 v[80:81], v[80:81], v[88:89]
	v_cvt_pk_bf16_f32 v78, v78, v79
	v_cvt_pk_bf16_f32 v79, v80, v81
	v_pk_mul_f32 v[80:81], v[188:189], v[0:1] op_sel_hi:[1,0]
	s_waitcnt lgkmcnt(0)
	v_pk_mul_f32 v[80:81], v[82:83], v[80:81]
	v_pk_mul_f32 v[82:83], v[186:187], v[0:1] op_sel_hi:[1,0]
	v_cvt_pk_bf16_f32 v80, v80, v81
	v_pk_mul_f32 v[82:83], v[84:85], v[82:83]
	s_nop 0
	v_cvt_pk_bf16_f32 v81, v82, v83
	ds_write2_b64 v105, v[78:79], v[80:81] offset0:10 offset1:11
	ds_read_b128 v[78:81], v104 offset:192
	ds_read_b128 v[82:85], v104 offset:208
	s_waitcnt lgkmcnt(1)
	v_pk_mul_f32 v[14:15], v[78:79], v[14:15]
	v_pk_mul_f32 v[12:13], v[80:81], v[12:13]
	v_cvt_pk_bf16_f32 v14, v14, v15
	v_cvt_pk_bf16_f32 v15, v12, v13
	v_pk_mul_f32 v[12:13], v[16:17], v[0:1] op_sel_hi:[1,0]
	v_pk_mul_f32 v[16:17], v[134:135], v[0:1] op_sel_hi:[1,0]
	s_waitcnt lgkmcnt(0)
	v_pk_mul_f32 v[12:13], v[82:83], v[12:13]
	v_pk_mul_f32 v[16:17], v[84:85], v[16:17]
	v_cvt_pk_bf16_f32 v12, v12, v13
	v_cvt_pk_bf16_f32 v13, v16, v17
	ds_write2_b64 v105, v[14:15], v[12:13] offset0:12 offset1:13
	ds_read_b128 v[12:15], v104 offset:224
	ds_read_b128 v[78:81], v104 offset:240
	v_pk_mul_f32 v[16:17], v[86:87], v[0:1] op_sel_hi:[1,0]
	v_lshrrev_b32_e32 v0, 2, v110
	v_and_b32_e32 v141, 8, v0
	v_and_b32_e32 v0, 0xffffffc0, v110
	s_waitcnt lgkmcnt(0)
	v_pk_mul_f32 v[8:9], v[78:79], v[8:9] op_sel:[0,1] op_sel_hi:[1,0]
	v_pk_mul_f32 v[6:7], v[80:81], v[6:7] op_sel:[0,1] op_sel_hi:[1,0]
	v_pk_mul_f32 v[12:13], v[12:13], v[16:17]
	v_pk_mul_f32 v[10:11], v[14:15], v[10:11]
	v_cvt_pk_bf16_f32 v8, v8, v9
	v_cvt_pk_bf16_f32 v9, v6, v7
	v_add_u32_e32 v142, 0, v0
	v_lshlrev_b32_e32 v0, 1, v111
	v_mul_u32_u24_e32 v6, 0x208, v141
	v_cvt_pk_bf16_f32 v12, v12, v13
	v_cvt_pk_bf16_f32 v13, v10, v11
	v_add3_u32 v0, v142, v0, v6
	ds_write2_b64 v105, v[12:13], v[8:9] offset0:14 offset1:15
	s_waitcnt lgkmcnt(0)
	s_barrier
	ds_read_u16 v6, v0
	ds_read_u16 v7, v0 offset:520
	ds_read_u16 v8, v0 offset:1040
	ds_read_u16 v9, v0 offset:1560
	ds_read_u16 v10, v0 offset:2080
	ds_read_u16 v11, v0 offset:2600
	ds_read_u16 v12, v0 offset:3120
	ds_read_u16 v13, v0 offset:3640
	s_waitcnt lgkmcnt(6)
	v_lshl_or_b32 v78, v7, 16, v6
	s_waitcnt lgkmcnt(4)
	v_lshl_or_b32 v79, v9, 16, v8
	s_waitcnt lgkmcnt(2)
	v_lshl_or_b32 v80, v11, 16, v10
	ds_read_u16 v6, v0 offset:8320
	ds_read_u16 v7, v0 offset:8840
	ds_read_u16 v8, v0 offset:9360
	ds_read_u16 v9, v0 offset:9880
	ds_read_u16 v10, v0 offset:10400
	ds_read_u16 v11, v0 offset:10920
	ds_read_u16 v85, v0 offset:11440
	ds_read_u16 v86, v0 offset:11960
	s_waitcnt lgkmcnt(8)
	v_lshl_or_b32 v81, v13, 16, v12
	s_waitcnt lgkmcnt(6)
	v_lshl_or_b32 v82, v7, 16, v6
	s_waitcnt lgkmcnt(4)
	v_lshl_or_b32 v83, v9, 16, v8
	s_waitcnt lgkmcnt(2)
	v_lshl_or_b32 v84, v11, 16, v10
	v_mfma_f32_32x32x16_bf16 v[2:17], v[78:81], v[2:5], 0
	s_waitcnt lgkmcnt(0)
	v_lshl_or_b32 v85, v86, 16, v85
	ds_read_u16 v87, v0 offset:16640
	ds_read_u16 v88, v0 offset:17160
	ds_read_u16 v89, v0 offset:17680
	ds_read_u16 v90, v0 offset:18200
	ds_read_u16 v91, v0 offset:18720
	ds_read_u16 v92, v0 offset:19240
	ds_read_u16 v93, v0 offset:19760
	ds_read_u16 v94, v0 offset:20280
	s_waitcnt lgkmcnt(6)
	v_lshl_or_b32 v86, v88, 16, v87
	s_waitcnt lgkmcnt(4)
	v_lshl_or_b32 v87, v90, 16, v89
	s_waitcnt lgkmcnt(2)
	v_lshl_or_b32 v88, v92, 16, v91
	s_waitcnt lgkmcnt(0)
	v_lshl_or_b32 v89, v94, 16, v93
	v_mfma_f32_32x32x16_bf16 v[2:17], v[82:85], v[26:29], v[2:17]
	ds_read_u16 v26, v0 offset:24960
	ds_read_u16 v27, v0 offset:25480
	ds_read_u16 v28, v0 offset:26000
	ds_read_u16 v29, v0 offset:26520
	ds_read_u16 v92, v0 offset:27040
	ds_read_u16 v93, v0 offset:27560
	ds_read_u16 v94, v0 offset:28080
	ds_read_u16 v95, v0 offset:28600
	s_waitcnt lgkmcnt(6)
	v_lshl_or_b32 v90, v27, 16, v26
	s_waitcnt lgkmcnt(4)
	v_lshl_or_b32 v91, v29, 16, v28
	s_waitcnt lgkmcnt(2)
	v_lshl_or_b32 v92, v93, 16, v92
	s_waitcnt lgkmcnt(0)
	v_lshl_or_b32 v93, v95, 16, v94
	v_mfma_f32_32x32x16_bf16 v[2:17], v[86:89], v[22:25], v[2:17]
	ds_read_u16 v22, v0 offset:33280
	ds_read_u16 v23, v0 offset:33800
	ds_read_u16 v24, v0 offset:34320
	ds_read_u16 v25, v0 offset:34840
	ds_read_u16 v26, v0 offset:35360
	ds_read_u16 v27, v0 offset:35880
	ds_read_u16 v28, v0 offset:36400
	ds_read_u16 v29, v0 offset:36920
	s_waitcnt lgkmcnt(6)
	v_lshl_or_b32 v94, v23, 16, v22
	s_waitcnt lgkmcnt(4)
	v_lshl_or_b32 v95, v25, 16, v24
	s_waitcnt lgkmcnt(2)
	v_lshl_or_b32 v96, v27, 16, v26
	s_waitcnt lgkmcnt(0)
	v_lshl_or_b32 v97, v29, 16, v28
	v_mfma_f32_32x32x16_bf16 v[2:17], v[90:93], v[18:21], v[2:17]
	ds_read_u16 v18, v0 offset:41600
	ds_read_u16 v19, v0 offset:42120
	ds_read_u16 v20, v0 offset:42640
	ds_read_u16 v21, v0 offset:43160
	ds_read_u16 v22, v0 offset:43680
	ds_read_u16 v23, v0 offset:44200
	ds_read_u16 v24, v0 offset:44720
	ds_read_u16 v25, v0 offset:45240
	s_waitcnt lgkmcnt(6)
	v_lshl_or_b32 v98, v19, 16, v18
	s_waitcnt lgkmcnt(4)
	v_lshl_or_b32 v99, v21, 16, v20
	s_waitcnt lgkmcnt(2)
	v_lshl_or_b32 v100, v23, 16, v22
	ds_read_u16 v18, v0 offset:49920
	ds_read_u16 v19, v0 offset:50440
	ds_read_u16 v20, v0 offset:50960
	ds_read_u16 v21, v0 offset:51480
	ds_read_u16 v22, v0 offset:52000
	ds_read_u16 v23, v0 offset:52520
	ds_read_u16 v26, v0 offset:53040
	ds_read_u16 v27, v0 offset:53560
	s_waitcnt lgkmcnt(8)
	v_lshl_or_b32 v101, v25, 16, v24
	v_mfma_f32_32x32x16_bf16 v[2:17], v[94:97], v[66:69], v[2:17]
	s_waitcnt lgkmcnt(6)
	v_lshl_or_b32 v66, v19, 16, v18
	s_waitcnt lgkmcnt(4)
	v_lshl_or_b32 v67, v21, 16, v20
	s_waitcnt lgkmcnt(2)
	v_lshl_or_b32 v68, v23, 16, v22
	ds_read_u16 v18, v0 offset:58240
	ds_read_u16 v19, v0 offset:58760
	ds_read_u16 v20, v0 offset:59280
	ds_read_u16 v21, v0 offset:59800
	ds_read_u16 v22, v0 offset:60320
	ds_read_u16 v23, v0 offset:60840
	ds_read_u16 v24, v0 offset:61360
	ds_read_u16 v0, v0 offset:61880
	s_waitcnt lgkmcnt(8)
	v_lshl_or_b32 v69, v27, 16, v26
	s_waitcnt lgkmcnt(6)
	v_lshl_or_b32 v102, v19, 16, v18
	s_waitcnt lgkmcnt(4)
	v_lshl_or_b32 v103, v21, 16, v20
	s_waitcnt lgkmcnt(2)
	v_lshl_or_b32 v104, v23, 16, v22
	s_waitcnt lgkmcnt(0)
	v_lshl_or_b32 v105, v0, 16, v24
	v_mfma_f32_32x32x16_bf16 v[18:33], v[78:81], v[30:33], 0
	v_lshl_or_b32 v0, s0, 7, v111
	v_mfma_f32_32x32x16_bf16 v[18:33], v[82:85], v[50:53], v[18:33]
	global_load_dwordx4 v[50:53], v[108:109], off offset:1024
	v_mfma_f32_32x32x16_bf16 v[18:33], v[86:89], v[46:49], v[18:33]
	v_mfma_f32_32x32x16_bf16 v[18:33], v[90:93], v[42:45], v[18:33]
	global_load_dwordx4 v[42:45], v[108:109], off
	v_mfma_f32_32x32x16_bf16 v[2:17], v[98:101], v[62:65], v[2:17]
	v_mfma_f32_32x32x16_bf16 v[2:17], v[66:69], v[54:57], v[2:17]
	global_load_dwordx4 v[54:57], v[108:109], off offset:2048
	v_mfma_f32_32x32x16_bf16 v[18:33], v[94:97], v[38:41], v[18:33]
	v_mfma_f32_32x32x16_bf16 v[2:17], v[102:105], v[58:61], v[2:17]
	global_load_dwordx4 v[58:61], v[108:109], off offset:3072
	v_add_co_u32_e32 v108, vcc, s1, v106
	s_movk_i32 s1, 0x5000
	s_nop 0
	v_addc_co_u32_e32 v109, vcc, 0, v107, vcc
	global_load_dwordx4 v[62:65], v[108:109], off offset:-4096
	v_mfma_f32_32x32x16_bf16 v[18:33], v[98:101], v[34:37], v[18:33]
	v_add_co_u32_e32 v128, vcc, s1, v106
	s_movk_i32 s1, 0x7000
	s_nop 0
	v_addc_co_u32_e32 v129, vcc, 0, v107, vcc
	v_add_co_u32_e32 v136, vcc, s1, v106
	s_waitcnt vmcnt(6)
	v_mfma_f32_32x32x16_bf16 v[18:33], v[66:69], v[74:77], v[18:33]
	v_addc_co_u32_e32 v137, vcc, 0, v107, vcc
	v_cmp_gt_i32_e32 vcc, s46, v110
	s_waitcnt vmcnt(5)
	v_mfma_f32_32x32x16_bf16 v[18:33], v[102:105], v[70:73], v[18:33]
	global_load_dwordx4 v[70:73], v[128:129], off offset:1024
	global_load_dwordx4 v[74:77], v[128:129], off offset:2048
	global_load_dwordx4 v[112:115], v[108:109], off
	global_load_dwordx4 v[116:119], v[108:109], off offset:1024
	global_load_dwordx4 v[120:123], v[108:109], off offset:2048
	global_load_dwordx4 v[124:127], v[108:109], off offset:3072
	s_waitcnt vmcnt(9)
	v_mfma_f32_32x32x16_bf16 v[34:49], v[78:81], v[42:45], 0
	v_mfma_f32_32x32x16_bf16 v[34:49], v[82:85], v[50:53], v[34:49]
	global_load_dwordx4 v[50:53], v[128:129], off offset:3072
	global_load_dwordx4 v[106:109], v[136:137], off
	s_nop 0
	global_load_dwordx4 v[128:131], v[136:137], off offset:1024
	global_load_dwordx4 v[132:135], v[136:137], off offset:2048
	s_nop 0
	global_load_dwordx4 v[136:139], v[136:137], off offset:3072
	s_barrier
	s_waitcnt vmcnt(13)
	v_mfma_f32_32x32x16_bf16 v[34:49], v[86:89], v[54:57], v[34:49]
	v_lshl_add_u64 v[54:55], v[0:1], 2, s[48:49]
	global_load_dword v0, v[54:55], off
	global_load_dword v140, v[54:55], off offset:128
	s_waitcnt vmcnt(14)
	v_mfma_f32_32x32x16_bf16 v[34:49], v[90:93], v[58:61], v[34:49]
	s_waitcnt vmcnt(13)
	v_mfma_f32_32x32x16_bf16 v[34:49], v[94:97], v[62:65], v[34:49]
	s_waitcnt vmcnt(12)
	v_mfma_f32_32x32x16_bf16 v[34:49], v[98:101], v[70:73], v[34:49]
	global_load_dword v70, v[54:55], off offset:256
	global_load_dword v72, v[54:55], off offset:384
	v_ashrrev_i32_e32 v143, 5, v110
	v_add_u32_e32 v143, s40, v143
	v_mov_b64_e32 v[144:145], s[24:25]
	v_mad_i64_i32 v[146:147], s[44:45], v143, s77, v[144:145]
	v_lshl_or_b32 v144, v111, 3, s28
	v_lshlrev_b32_e32 v144, 1, v144
	v_add_u32_e32 v144, s34, v144
	v_mov_b32_e32 v145, 0
	v_lshl_add_u64 v[146:147], v[146:147], 0, v[144:145]
	s_mov_b64 s[44:45], 0x28000
	global_load_dwordx4 v[148:151], v[146:147], off offset:-4096
	global_load_dwordx4 v[180:183], v[146:147], off
	v_lshl_add_u64 v[146:147], v[146:147], 0, s[44:45]
	global_load_dwordx4 v[152:155], v[146:147], off offset:-4096
	global_load_dwordx4 v[184:187], v[146:147], off
	v_lshl_add_u64 v[146:147], v[146:147], 0, s[44:45]
	global_load_dwordx4 v[156:159], v[146:147], off offset:-4096
	global_load_dwordx4 v[188:191], v[146:147], off
	v_lshl_add_u64 v[146:147], v[146:147], 0, s[44:45]
	global_load_dwordx4 v[160:163], v[146:147], off offset:-4096
	global_load_dwordx4 v[192:195], v[146:147], off
	v_lshl_add_u64 v[146:147], v[146:147], 0, s[44:45]
	global_load_dwordx4 v[164:167], v[146:147], off offset:-4096
	global_load_dwordx4 v[196:199], v[146:147], off
	v_lshl_add_u64 v[146:147], v[146:147], 0, s[44:45]
	global_load_dwordx4 v[168:171], v[146:147], off offset:-4096
	global_load_dwordx4 v[212:215], v[146:147], off
	v_lshl_add_u64 v[146:147], v[146:147], 0, s[44:45]
	global_load_dwordx4 v[172:175], v[146:147], off offset:-4096
	global_load_dwordx4 v[216:219], v[146:147], off
	v_lshl_add_u64 v[146:147], v[146:147], 0, s[44:45]
	global_load_dwordx4 v[176:179], v[146:147], off offset:-4096
	global_load_dwordx4 v[220:223], v[146:147], off
	v_mul_u32_u24_e32 v54, 0x210, v111
	v_add3_u32 v71, v142, v141, v54
	s_waitcnt vmcnt(19)
	v_pk_add_f32 v[2:3], v[0:1], v[2:3] op_sel_hi:[0,1]
	v_mfma_f32_32x32x16_bf16 v[34:49], v[66:69], v[74:77], v[34:49]
	v_add_f32_e64 v4, v0, v4
	v_add_f32_e64 v5, v0, v5
	v_cvt_pk_bf16_f32 v2, v2, v3
	v_cvt_pk_bf16_f32 v3, v4, v5
	v_add_f32_e64 v4, v0, v6
	v_add_f32_e64 v5, v0, v7
	v_pk_add_f32 v[6:7], v[0:1], v[8:9] op_sel_hi:[0,1]
	v_cvt_pk_bf16_f32 v4, v4, v5
	v_cvt_pk_bf16_f32 v5, v6, v7
	v_mfma_f32_32x32x16_bf16 v[34:49], v[102:105], v[50:53], v[34:49]
	ds_write2_b64 v71, v[2:3], v[4:5] offset1:2
	v_add_f32_e64 v2, v0, v10
	v_add_f32_e64 v3, v0, v11
	v_add_f32_e64 v4, v0, v12
	v_add_f32_e64 v5, v0, v13
	v_cvt_pk_bf16_f32 v2, v2, v3
	v_cvt_pk_bf16_f32 v3, v4, v5
	v_pk_add_f32 v[4:5], v[0:1], v[14:15] op_sel_hi:[0,1]
	v_pk_add_f32 v[6:7], v[0:1], v[16:17] op_sel_hi:[0,1]
	v_mfma_f32_32x32x16_bf16 v[50:65], v[78:81], v[112:115], 0
	v_cvt_pk_bf16_f32 v4, v4, v5
	v_cvt_pk_bf16_f32 v5, v6, v7
	ds_write2_b64 v71, v[2:3], v[4:5] offset0:4 offset1:6
	s_waitcnt vmcnt(18)
	v_add_f32_e64 v2, v140, v18
	v_add_f32_e64 v3, v140, v19
	v_pk_add_f32 v[4:5], v[140:141], v[20:21] op_sel_hi:[0,1]
	v_cvt_pk_bf16_f32 v2, v2, v3
	v_cvt_pk_bf16_f32 v3, v4, v5
	v_mfma_f32_32x32x16_bf16 v[50:65], v[82:85], v[116:119], v[50:65]
	v_add_f32_e64 v4, v140, v22
	v_add_f32_e64 v5, v140, v23
	v_add_f32_e64 v6, v140, v24
	v_add_f32_e64 v7, v140, v25
	v_cvt_pk_bf16_f32 v4, v4, v5
	v_cvt_pk_bf16_f32 v5, v6, v7
	v_add_u32_e32 v0, 0x4000, v71
	ds_write2_b64 v0, v[2:3], v[4:5] offset0:64 offset1:66
	v_pk_add_f32 v[2:3], v[140:141], v[26:27] op_sel_hi:[0,1]
	v_mfma_f32_32x32x16_bf16 v[50:65], v[86:89], v[120:123], v[50:65]
	v_add_f32_e64 v4, v140, v28
	v_add_f32_e64 v5, v140, v29
	v_cvt_pk_bf16_f32 v2, v2, v3
	v_cvt_pk_bf16_f32 v3, v4, v5
	v_add_f32_e64 v4, v140, v30
	v_add_f32_e64 v5, v140, v31
	v_pk_add_f32 v[6:7], v[140:141], v[32:33] op_sel_hi:[0,1]
	v_cvt_pk_bf16_f32 v4, v4, v5
	v_cvt_pk_bf16_f32 v5, v6, v7
	v_mfma_f32_32x32x16_bf16 v[50:65], v[90:93], v[124:127], v[50:65]
	ds_write2_b64 v0, v[2:3], v[4:5] offset0:68 offset1:70
	s_waitcnt vmcnt(17)
	v_add_f32_e64 v2, v70, v34
	v_add_f32_e64 v3, v70, v35
	v_add_f32_e64 v4, v70, v36
	v_add_f32_e64 v5, v70, v37
	v_cvt_pk_bf16_f32 v2, v2, v3
	v_cvt_pk_bf16_f32 v3, v4, v5
	v_pk_add_f32 v[4:5], v[70:71], v[38:39] op_sel_hi:[0,1]
	v_pk_add_f32 v[6:7], v[70:71], v[40:41] op_sel_hi:[0,1]
	v_mfma_f32_32x32x16_bf16 v[50:65], v[94:97], v[106:109], v[50:65]
	v_cvt_pk_bf16_f32 v4, v4, v5
	v_cvt_pk_bf16_f32 v5, v6, v7
	v_add_u32_e32 v0, 0x8000, v71
	ds_write2_b64 v0, v[2:3], v[4:5] offset0:128 offset1:130
	v_add_f32_e64 v2, v70, v42
	v_add_f32_e64 v3, v70, v43
	v_pk_add_f32 v[4:5], v[70:71], v[44:45] op_sel_hi:[0,1]
	v_cvt_pk_bf16_f32 v2, v2, v3
	v_mfma_f32_32x32x16_bf16 v[50:65], v[98:101], v[128:131], v[50:65]
	v_cvt_pk_bf16_f32 v3, v4, v5
	v_add_f32_e64 v4, v70, v46
	v_add_f32_e64 v5, v70, v47
	v_add_f32_e64 v6, v70, v48
	v_add_f32_e64 v7, v70, v49
	v_cvt_pk_bf16_f32 v4, v4, v5
	v_cvt_pk_bf16_f32 v5, v6, v7
	ds_write2_b64 v0, v[2:3], v[4:5] offset0:132 offset1:134
	v_add_u32_e32 v0, 0xc000, v71
	v_mfma_f32_32x32x16_bf16 v[50:65], v[66:69], v[132:135], v[50:65]
	v_mfma_f32_32x32x16_bf16 v[50:65], v[102:105], v[136:139], v[50:65]
	s_waitcnt vmcnt(16)
	s_nop 10
	v_pk_add_f32 v[2:3], v[72:73], v[50:51] op_sel_hi:[0,1]
	v_pk_add_f32 v[4:5], v[72:73], v[52:53] op_sel_hi:[0,1]
	v_cvt_pk_bf16_f32 v2, v2, v3
	v_cvt_pk_bf16_f32 v3, v4, v5
	v_pk_add_f32 v[4:5], v[72:73], v[54:55] op_sel_hi:[0,1]
	v_pk_add_f32 v[6:7], v[72:73], v[56:57] op_sel_hi:[0,1]
	v_cvt_pk_bf16_f32 v4, v4, v5
	v_cvt_pk_bf16_f32 v5, v6, v7
	ds_write2_b64 v0, v[2:3], v[4:5] offset0:192 offset1:194
	v_pk_add_f32 v[2:3], v[72:73], v[58:59] op_sel_hi:[0,1]
	v_pk_add_f32 v[4:5], v[72:73], v[60:61] op_sel_hi:[0,1]
	v_cvt_pk_bf16_f32 v2, v2, v3
	v_cvt_pk_bf16_f32 v3, v4, v5
	v_pk_add_f32 v[4:5], v[72:73], v[62:63] op_sel_hi:[0,1]
	v_pk_add_f32 v[6:7], v[72:73], v[64:65] op_sel_hi:[0,1]
	v_cvt_pk_bf16_f32 v4, v4, v5
	v_cvt_pk_bf16_f32 v5, v6, v7
	ds_write2_b64 v0, v[2:3], v[4:5] offset0:196 offset1:198
	s_waitcnt lgkmcnt(0)
	s_barrier
	s_and_saveexec_b64 s[0:1], vcc
	s_cbranch_execz .LBB0_305
	v_max_i32_e32 v2, 0xe00, v110
	v_sub_u32_e32 v2, v2, v110
	v_add_u32_e32 v7, 0x1ff, v2
	v_lshl_or_b32 v0, v111, 3, s28
	v_and_b32_e32 v2, 0x200, v7
	v_lshl_add_u32 v6, v111, 4, 0
	v_cmp_eq_u32_e32 vcc, 0, v2
	v_lshlrev_b32_e32 v0, 1, v0
	s_and_saveexec_b64 s[28:29], vcc
	s_cbranch_execz .LBB0_311
	v_ashrrev_i32_e32 v2, 5, v110
	v_add_u32_e32 v8, s40, v2
	v_mov_b64_e32 v[10:11], s[24:25]
	v_mad_i64_i32 v[10:11], s[44:45], v8, s77, v[10:11]
	v_lshl_add_u64 v[10:11], v[10:11], 0, v[0:1]
	v_add_co_u32_e32 v14, vcc, s34, v10
	v_mad_u64_u32 v[2:3], s[44:45], v2, s69, v[6:7]
	s_nop 0
	v_addc_co_u32_e32 v15, vcc, 0, v11, vcc
	ds_read_b128 v[2:5], v2
	global_load_dwordx4 v[10:13], v[14:15], off offset:-4096
	s_nop 0
	global_load_dwordx4 v[14:17], v[14:15], off
	v_ashrrev_i32_e32 v9, 31, v8
	v_lshlrev_b64 v[8:9], 12, v[8:9]
	v_lshl_add_u64 v[8:9], s[18:19], 0, v[8:9]
	s_waitcnt lgkmcnt(0)
	v_lshlrev_b32_e32 v24, 16, v2
	v_and_b32_e32 v25, 0xffff0000, v2
	v_lshl_add_u64 v[8:9], v[8:9], 0, v[0:1]
	v_add_co_u32_e32 v8, vcc, 0x11848000, v8
	v_add_u32_e32 v110, 0x200, v110
	s_nop 0
	v_addc_co_u32_e32 v9, vcc, 0, v9, vcc
	s_waitcnt vmcnt(1)
	v_lshlrev_b32_e32 v22, 16, v10
	s_waitcnt vmcnt(0)
	v_lshlrev_b32_e32 v18, 16, v14
	v_and_b32_e32 v19, 0xffff0000, v14
	v_mul_f32_e32 v14, 0xbfb8aa3b, v18
	v_mul_f32_e32 v2, 0xbfb8aa3b, v19
	v_exp_f32_e32 v14, v14
	v_exp_f32_e32 v2, v2
	v_and_b32_e32 v23, 0xffff0000, v10
	v_pk_mul_f32 v[22:23], v[24:25], v[22:23]
	v_add_f32_e32 v14, 1.0, v14
	v_add_f32_e32 v2, 1.0, v2
	v_rcp_f32_e32 v20, v14
	v_rcp_f32_e32 v21, v2
	v_lshlrev_b32_e32 v14, 16, v15
	v_and_b32_e32 v15, 0xffff0000, v15
	v_mul_f32_e32 v10, 0xbfb8aa3b, v14
	v_pk_mul_f32 v[18:19], v[20:21], v[18:19]
	v_lshlrev_b32_e32 v20, 16, v3
	v_and_b32_e32 v21, 0xffff0000, v3
	v_mul_f32_e32 v3, 0xbfb8aa3b, v15
	v_exp_f32_e32 v10, v10
	v_exp_f32_e32 v3, v3
	v_pk_mul_f32 v[18:19], v[22:23], v[18:19]
	v_add_f32_e32 v10, 1.0, v10
	v_add_f32_e32 v3, 1.0, v3
	v_cvt_pk_bf16_f32 v2, v18, v19
	v_rcp_f32_e32 v10, v10
	v_lshlrev_b32_e32 v18, 16, v11
	v_and_b32_e32 v19, 0xffff0000, v11
	v_rcp_f32_e32 v11, v3
	v_pk_mul_f32 v[18:19], v[20:21], v[18:19]
	v_lshlrev_b32_e32 v20, 16, v4
	v_and_b32_e32 v21, 0xffff0000, v4
	v_pk_mul_f32 v[10:11], v[10:11], v[14:15]
	s_nop 0
	v_pk_mul_f32 v[10:11], v[18:19], v[10:11]
	v_lshlrev_b32_e32 v18, 16, v12
	v_cvt_pk_bf16_f32 v3, v10, v11
	v_lshlrev_b32_e32 v10, 16, v16
	v_and_b32_e32 v11, 0xffff0000, v16
	v_mul_f32_e32 v14, 0xbfb8aa3b, v10
	v_mul_f32_e32 v4, 0xbfb8aa3b, v11
	v_exp_f32_e32 v14, v14
	v_exp_f32_e32 v4, v4
	v_and_b32_e32 v19, 0xffff0000, v12
	v_pk_mul_f32 v[18:19], v[20:21], v[18:19]
	v_add_f32_e32 v14, 1.0, v14
	v_add_f32_e32 v4, 1.0, v4
	v_rcp_f32_e32 v14, v14
	v_rcp_f32_e32 v15, v4
	v_lshlrev_b32_e32 v16, 16, v5
	v_pk_mul_f32 v[10:11], v[14:15], v[10:11]
	s_nop 0
	v_pk_mul_f32 v[10:11], v[18:19], v[10:11]
	v_lshlrev_b32_e32 v14, 16, v13
	v_cvt_pk_bf16_f32 v4, v10, v11
	v_lshlrev_b32_e32 v10, 16, v17
	v_and_b32_e32 v11, 0xffff0000, v17
	v_mul_f32_e32 v12, 0xbfb8aa3b, v10
	v_and_b32_e32 v17, 0xffff0000, v5
	v_mul_f32_e32 v5, 0xbfb8aa3b, v11
	v_exp_f32_e32 v12, v12
	v_exp_f32_e32 v5, v5
	v_and_b32_e32 v15, 0xffff0000, v13
	v_pk_mul_f32 v[14:15], v[16:17], v[14:15]
	v_add_f32_e32 v12, 1.0, v12
	v_add_f32_e32 v5, 1.0, v5
	v_rcp_f32_e32 v12, v12
	v_rcp_f32_e32 v13, v5
	s_nop 0
	v_pk_mul_f32 v[10:11], v[12:13], v[10:11]
	s_nop 0
	v_pk_mul_f32 v[10:11], v[14:15], v[10:11]
	s_nop 0
	v_cvt_pk_bf16_f32 v5, v10, v11
	global_store_dwordx4 v[8:9], v[2:5], off offset:2048

.LBB0_313:
	v_ashrrev_i32_e32 v2, 5, v110
	v_add_u32_e32 v4, s40, v2
	v_mad_u64_u32 v[2:3], s[44:45], v2, s69, v[6:7]
	s_mov_b64 s[28:29], 0x10000
	ds_read_b128 v[112:115], v2
	ds_read_b128 v[116:119], v2 offset:8448
	ds_read_b128 v[120:123], v2 offset:16896
	ds_read_b128 v[124:127], v2 offset:25344
	ds_read_b128 v[128:131], v2 offset:33792
	ds_read_b128 v[132:135], v2 offset:42240
	ds_read_b128 v[136:139], v2 offset:50688
	ds_read_b128 v[140:143], v2 offset:59136
	v_ashrrev_i32_e32 v5, 31, v4
	v_lshlrev_b64 v[4:5], 12, v[4:5]
	v_lshl_add_u64 v[4:5], s[18:19], 0, v[4:5]
	v_lshl_add_u64 v[4:5], v[4:5], 0, v[0:1]
	v_add_co_u32_e32 v4, vcc, 0x11848000, v4
	s_nop 1
	v_addc_co_u32_e32 v5, vcc, 0, v5, vcc
	s_waitcnt lgkmcnt(0)
	s_waitcnt vmcnt(14)
	v_lshlrev_b32_e32 v26, 16, v112
	v_and_b32_e32 v27, 0xffff0000, v112
	v_lshlrev_b32_e32 v24, 16, v148
	v_lshlrev_b32_e32 v20, 16, v180
	v_mul_f32_e32 v7, 0xbfb8aa3b, v20
	v_exp_f32_e32 v7, v7
	v_and_b32_e32 v21, 0xffff0000, v180
	v_lshlrev_b32_e32 v180, 16, v181
	v_and_b32_e32 v181, 0xffff0000, v181
	v_add_f32_e32 v7, 1.0, v7
	v_rcp_f32_e32 v22, v7
	v_mul_f32_e32 v7, 0xbfb8aa3b, v21
	v_exp_f32_e32 v7, v7
	v_and_b32_e32 v25, 0xffff0000, v148
	v_pk_mul_f32 v[24:25], v[26:27], v[24:25]
	v_add_f32_e32 v7, 1.0, v7
	v_rcp_f32_e32 v23, v7
	v_mul_f32_e32 v7, 0xbfb8aa3b, v180
	v_exp_f32_e32 v7, v7
	v_pk_mul_f32 v[20:21], v[22:23], v[20:21]
	s_nop 0
	v_pk_mul_f32 v[20:21], v[24:25], v[20:21]
	v_add_f32_e32 v7, 1.0, v7
	v_rcp_f32_e32 v148, v7
	v_mul_f32_e32 v7, 0xbfb8aa3b, v181
	v_exp_f32_e32 v7, v7
	v_cvt_pk_bf16_f32 v112, v20, v21
	v_lshlrev_b32_e32 v20, 16, v149
	v_and_b32_e32 v21, 0xffff0000, v149
	v_add_f32_e32 v7, 1.0, v7
	v_rcp_f32_e32 v149, v7
	v_lshlrev_b32_e32 v22, 16, v113
	v_and_b32_e32 v23, 0xffff0000, v113
	v_pk_mul_f32 v[20:21], v[22:23], v[20:21]
	v_pk_mul_f32 v[148:149], v[148:149], v[180:181]
	v_lshlrev_b32_e32 v22, 16, v114
	v_pk_mul_f32 v[148:149], v[20:21], v[148:149]
	v_lshlrev_b32_e32 v20, 16, v150
	v_cvt_pk_bf16_f32 v113, v148, v149
	v_lshlrev_b32_e32 v148, 16, v182
	v_mul_f32_e32 v7, 0xbfb8aa3b, v148
	v_exp_f32_e32 v7, v7
	v_and_b32_e32 v149, 0xffff0000, v182
	v_and_b32_e32 v21, 0xffff0000, v150
	v_and_b32_e32 v23, 0xffff0000, v114
	v_add_f32_e32 v7, 1.0, v7
	v_rcp_f32_e32 v180, v7
	v_mul_f32_e32 v7, 0xbfb8aa3b, v149
	v_exp_f32_e32 v7, v7
	v_pk_mul_f32 v[20:21], v[22:23], v[20:21]
	v_lshlrev_b32_e32 v182, 16, v115
	v_add_f32_e32 v7, 1.0, v7
	v_rcp_f32_e32 v181, v7
	s_nop 0
	v_pk_mul_f32 v[148:149], v[180:181], v[148:149]
	s_nop 0
	v_pk_mul_f32 v[148:149], v[20:21], v[148:149]
	v_lshlrev_b32_e32 v180, 16, v151
	v_cvt_pk_bf16_f32 v114, v148, v149
	v_lshlrev_b32_e32 v148, 16, v183
	v_mul_f32_e32 v7, 0xbfb8aa3b, v148
	v_exp_f32_e32 v7, v7
	v_and_b32_e32 v149, 0xffff0000, v183
	v_and_b32_e32 v181, 0xffff0000, v151
	v_and_b32_e32 v183, 0xffff0000, v115
	v_add_f32_e32 v7, 1.0, v7
	v_rcp_f32_e32 v150, v7
	v_mul_f32_e32 v7, 0xbfb8aa3b, v149
	v_exp_f32_e32 v7, v7
	v_pk_mul_f32 v[180:181], v[182:183], v[180:181]
	v_add_f32_e32 v7, 1.0, v7
	v_rcp_f32_e32 v151, v7
	s_nop 0
	v_pk_mul_f32 v[148:149], v[150:151], v[148:149]
	s_nop 0
	v_pk_mul_f32 v[148:149], v[180:181], v[148:149]
	s_nop 0
	v_cvt_pk_bf16_f32 v115, v148, v149
	global_store_dwordx4 v[4:5], v[112:115], off offset:2048
	v_lshl_add_u64 v[4:5], v[4:5], 0, s[28:29]
	s_waitcnt vmcnt(13)
	v_lshlrev_b32_e32 v26, 16, v116
	v_and_b32_e32 v27, 0xffff0000, v116
	v_lshlrev_b32_e32 v24, 16, v152
	v_lshlrev_b32_e32 v20, 16, v184
	v_mul_f32_e32 v7, 0xbfb8aa3b, v20
	v_exp_f32_e32 v7, v7
	v_and_b32_e32 v21, 0xffff0000, v184
	v_lshlrev_b32_e32 v184, 16, v185
	v_and_b32_e32 v185, 0xffff0000, v185
	v_add_f32_e32 v7, 1.0, v7
	v_rcp_f32_e32 v22, v7
	v_mul_f32_e32 v7, 0xbfb8aa3b, v21
	v_exp_f32_e32 v7, v7
	v_and_b32_e32 v25, 0xffff0000, v152
	v_pk_mul_f32 v[24:25], v[26:27], v[24:25]
	v_add_f32_e32 v7, 1.0, v7
	v_rcp_f32_e32 v23, v7
	v_mul_f32_e32 v7, 0xbfb8aa3b, v184
	v_exp_f32_e32 v7, v7
	v_pk_mul_f32 v[20:21], v[22:23], v[20:21]
	s_nop 0
	v_pk_mul_f32 v[20:21], v[24:25], v[20:21]
	v_add_f32_e32 v7, 1.0, v7
	v_rcp_f32_e32 v152, v7
	v_mul_f32_e32 v7, 0xbfb8aa3b, v185
	v_exp_f32_e32 v7, v7
	v_cvt_pk_bf16_f32 v116, v20, v21
	v_lshlrev_b32_e32 v20, 16, v153
	v_and_b32_e32 v21, 0xffff0000, v153
	v_add_f32_e32 v7, 1.0, v7
	v_rcp_f32_e32 v153, v7
	v_lshlrev_b32_e32 v22, 16, v117
	v_and_b32_e32 v23, 0xffff0000, v117
	v_pk_mul_f32 v[20:21], v[22:23], v[20:21]
	v_pk_mul_f32 v[152:153], v[152:153], v[184:185]
	v_lshlrev_b32_e32 v22, 16, v118
	v_pk_mul_f32 v[152:153], v[20:21], v[152:153]
	v_lshlrev_b32_e32 v20, 16, v154
	v_cvt_pk_bf16_f32 v117, v152, v153
	v_lshlrev_b32_e32 v152, 16, v186
	v_mul_f32_e32 v7, 0xbfb8aa3b, v152
	v_exp_f32_e32 v7, v7
	v_and_b32_e32 v153, 0xffff0000, v186
	v_and_b32_e32 v21, 0xffff0000, v154
	v_and_b32_e32 v23, 0xffff0000, v118
	v_add_f32_e32 v7, 1.0, v7
	v_rcp_f32_e32 v184, v7
	v_mul_f32_e32 v7, 0xbfb8aa3b, v153
	v_exp_f32_e32 v7, v7
	v_pk_mul_f32 v[20:21], v[22:23], v[20:21]
	v_lshlrev_b32_e32 v186, 16, v119
	v_add_f32_e32 v7, 1.0, v7
	v_rcp_f32_e32 v185, v7
	s_nop 0
	v_pk_mul_f32 v[152:153], v[184:185], v[152:153]
	s_nop 0
	v_pk_mul_f32 v[152:153], v[20:21], v[152:153]
	v_lshlrev_b32_e32 v184, 16, v155
	v_cvt_pk_bf16_f32 v118, v152, v153
	v_lshlrev_b32_e32 v152, 16, v187
	v_mul_f32_e32 v7, 0xbfb8aa3b, v152
	v_exp_f32_e32 v7, v7
	v_and_b32_e32 v153, 0xffff0000, v187
	v_and_b32_e32 v185, 0xffff0000, v155
	v_and_b32_e32 v187, 0xffff0000, v119
	v_add_f32_e32 v7, 1.0, v7
	v_rcp_f32_e32 v154, v7
	v_mul_f32_e32 v7, 0xbfb8aa3b, v153
	v_exp_f32_e32 v7, v7
	v_pk_mul_f32 v[184:185], v[186:187], v[184:185]
	v_add_f32_e32 v7, 1.0, v7
	v_rcp_f32_e32 v155, v7
	s_nop 0
	v_pk_mul_f32 v[152:153], v[154:155], v[152:153]
	s_nop 0
	v_pk_mul_f32 v[152:153], v[184:185], v[152:153]
	s_nop 0
	v_cvt_pk_bf16_f32 v119, v152, v153
	global_store_dwordx4 v[4:5], v[116:119], off offset:2048
	v_lshl_add_u64 v[4:5], v[4:5], 0, s[28:29]
	s_waitcnt vmcnt(12)
	v_lshlrev_b32_e32 v26, 16, v120
	v_and_b32_e32 v27, 0xffff0000, v120
	v_lshlrev_b32_e32 v24, 16, v156
	v_lshlrev_b32_e32 v20, 16, v188
	v_mul_f32_e32 v7, 0xbfb8aa3b, v20
	v_exp_f32_e32 v7, v7
	v_and_b32_e32 v21, 0xffff0000, v188
	v_lshlrev_b32_e32 v188, 16, v189
	v_and_b32_e32 v189, 0xffff0000, v189
	v_add_f32_e32 v7, 1.0, v7
	v_rcp_f32_e32 v22, v7
	v_mul_f32_e32 v7, 0xbfb8aa3b, v21
	v_exp_f32_e32 v7, v7
	v_and_b32_e32 v25, 0xffff0000, v156
	v_pk_mul_f32 v[24:25], v[26:27], v[24:25]
	v_add_f32_e32 v7, 1.0, v7
	v_rcp_f32_e32 v23, v7
	v_mul_f32_e32 v7, 0xbfb8aa3b, v188
	v_exp_f32_e32 v7, v7
	v_pk_mul_f32 v[20:21], v[22:23], v[20:21]
	s_nop 0
	v_pk_mul_f32 v[20:21], v[24:25], v[20:21]
	v_add_f32_e32 v7, 1.0, v7
	v_rcp_f32_e32 v156, v7
	v_mul_f32_e32 v7, 0xbfb8aa3b, v189
	v_exp_f32_e32 v7, v7
	v_cvt_pk_bf16_f32 v120, v20, v21
	v_lshlrev_b32_e32 v20, 16, v157
	v_and_b32_e32 v21, 0xffff0000, v157
	v_add_f32_e32 v7, 1.0, v7
	v_rcp_f32_e32 v157, v7
	v_lshlrev_b32_e32 v22, 16, v121
	v_and_b32_e32 v23, 0xffff0000, v121
	v_pk_mul_f32 v[20:21], v[22:23], v[20:21]
	v_pk_mul_f32 v[156:157], v[156:157], v[188:189]
	v_lshlrev_b32_e32 v22, 16, v122
	v_pk_mul_f32 v[156:157], v[20:21], v[156:157]
	v_lshlrev_b32_e32 v20, 16, v158
	v_cvt_pk_bf16_f32 v121, v156, v157
	v_lshlrev_b32_e32 v156, 16, v190
	v_mul_f32_e32 v7, 0xbfb8aa3b, v156
	v_exp_f32_e32 v7, v7
	v_and_b32_e32 v157, 0xffff0000, v190
	v_and_b32_e32 v21, 0xffff0000, v158
	v_and_b32_e32 v23, 0xffff0000, v122
	v_add_f32_e32 v7, 1.0, v7
	v_rcp_f32_e32 v188, v7
	v_mul_f32_e32 v7, 0xbfb8aa3b, v157
	v_exp_f32_e32 v7, v7
	v_pk_mul_f32 v[20:21], v[22:23], v[20:21]
	v_lshlrev_b32_e32 v190, 16, v123
	v_add_f32_e32 v7, 1.0, v7
	v_rcp_f32_e32 v189, v7
	s_nop 0
	v_pk_mul_f32 v[156:157], v[188:189], v[156:157]
	s_nop 0
	v_pk_mul_f32 v[156:157], v[20:21], v[156:157]
	v_lshlrev_b32_e32 v188, 16, v159
	v_cvt_pk_bf16_f32 v122, v156, v157
	v_lshlrev_b32_e32 v156, 16, v191
	v_mul_f32_e32 v7, 0xbfb8aa3b, v156
	v_exp_f32_e32 v7, v7
	v_and_b32_e32 v157, 0xffff0000, v191
	v_and_b32_e32 v189, 0xffff0000, v159
	v_and_b32_e32 v191, 0xffff0000, v123
	v_add_f32_e32 v7, 1.0, v7
	v_rcp_f32_e32 v158, v7
	v_mul_f32_e32 v7, 0xbfb8aa3b, v157
	v_exp_f32_e32 v7, v7
	v_pk_mul_f32 v[188:189], v[190:191], v[188:189]
	v_add_f32_e32 v7, 1.0, v7
	v_rcp_f32_e32 v159, v7
	s_nop 0
	v_pk_mul_f32 v[156:157], v[158:159], v[156:157]
	s_nop 0
	v_pk_mul_f32 v[156:157], v[188:189], v[156:157]
	s_nop 0
	v_cvt_pk_bf16_f32 v123, v156, v157
	global_store_dwordx4 v[4:5], v[120:123], off offset:2048
	v_lshl_add_u64 v[4:5], v[4:5], 0, s[28:29]
	s_waitcnt vmcnt(11)
	v_lshlrev_b32_e32 v26, 16, v124
	v_and_b32_e32 v27, 0xffff0000, v124
	v_lshlrev_b32_e32 v24, 16, v160
	v_lshlrev_b32_e32 v20, 16, v192
	v_mul_f32_e32 v7, 0xbfb8aa3b, v20
	v_exp_f32_e32 v7, v7
	v_and_b32_e32 v21, 0xffff0000, v192
	v_lshlrev_b32_e32 v192, 16, v193
	v_and_b32_e32 v193, 0xffff0000, v193
	v_add_f32_e32 v7, 1.0, v7
	v_rcp_f32_e32 v22, v7
	v_mul_f32_e32 v7, 0xbfb8aa3b, v21
	v_exp_f32_e32 v7, v7
	v_and_b32_e32 v25, 0xffff0000, v160
	v_pk_mul_f32 v[24:25], v[26:27], v[24:25]
	v_add_f32_e32 v7, 1.0, v7
	v_rcp_f32_e32 v23, v7
	v_mul_f32_e32 v7, 0xbfb8aa3b, v192
	v_exp_f32_e32 v7, v7
	v_pk_mul_f32 v[20:21], v[22:23], v[20:21]
	s_nop 0
	v_pk_mul_f32 v[20:21], v[24:25], v[20:21]
	v_add_f32_e32 v7, 1.0, v7
	v_rcp_f32_e32 v160, v7
	v_mul_f32_e32 v7, 0xbfb8aa3b, v193
	v_exp_f32_e32 v7, v7
	v_cvt_pk_bf16_f32 v124, v20, v21
	v_lshlrev_b32_e32 v20, 16, v161
	v_and_b32_e32 v21, 0xffff0000, v161
	v_add_f32_e32 v7, 1.0, v7
	v_rcp_f32_e32 v161, v7
	v_lshlrev_b32_e32 v22, 16, v125
	v_and_b32_e32 v23, 0xffff0000, v125
	v_pk_mul_f32 v[20:21], v[22:23], v[20:21]
	v_pk_mul_f32 v[160:161], v[160:161], v[192:193]
	v_lshlrev_b32_e32 v22, 16, v126
	v_pk_mul_f32 v[160:161], v[20:21], v[160:161]
	v_lshlrev_b32_e32 v20, 16, v162
	v_cvt_pk_bf16_f32 v125, v160, v161
	v_lshlrev_b32_e32 v160, 16, v194
	v_mul_f32_e32 v7, 0xbfb8aa3b, v160
	v_exp_f32_e32 v7, v7
	v_and_b32_e32 v161, 0xffff0000, v194
	v_and_b32_e32 v21, 0xffff0000, v162
	v_and_b32_e32 v23, 0xffff0000, v126
	v_add_f32_e32 v7, 1.0, v7
	v_rcp_f32_e32 v192, v7
	v_mul_f32_e32 v7, 0xbfb8aa3b, v161
	v_exp_f32_e32 v7, v7
	v_pk_mul_f32 v[20:21], v[22:23], v[20:21]
	v_lshlrev_b32_e32 v194, 16, v127
	v_add_f32_e32 v7, 1.0, v7
	v_rcp_f32_e32 v193, v7
	s_nop 0
	v_pk_mul_f32 v[160:161], v[192:193], v[160:161]
	s_nop 0
	v_pk_mul_f32 v[160:161], v[20:21], v[160:161]
	v_lshlrev_b32_e32 v192, 16, v163
	v_cvt_pk_bf16_f32 v126, v160, v161
	v_lshlrev_b32_e32 v160, 16, v195
	v_mul_f32_e32 v7, 0xbfb8aa3b, v160
	v_exp_f32_e32 v7, v7
	v_and_b32_e32 v161, 0xffff0000, v195
	v_and_b32_e32 v193, 0xffff0000, v163
	v_and_b32_e32 v195, 0xffff0000, v127
	v_add_f32_e32 v7, 1.0, v7
	v_rcp_f32_e32 v162, v7
	v_mul_f32_e32 v7, 0xbfb8aa3b, v161
	v_exp_f32_e32 v7, v7
	v_pk_mul_f32 v[192:193], v[194:195], v[192:193]
	v_add_f32_e32 v7, 1.0, v7
	v_rcp_f32_e32 v163, v7
	s_nop 0
	v_pk_mul_f32 v[160:161], v[162:163], v[160:161]
	s_nop 0
	v_pk_mul_f32 v[160:161], v[192:193], v[160:161]
	s_nop 0
	v_cvt_pk_bf16_f32 v127, v160, v161
	global_store_dwordx4 v[4:5], v[124:127], off offset:2048
	v_lshl_add_u64 v[4:5], v[4:5], 0, s[28:29]
	s_waitcnt vmcnt(10)
	v_lshlrev_b32_e32 v26, 16, v128
	v_and_b32_e32 v27, 0xffff0000, v128
	v_lshlrev_b32_e32 v24, 16, v164
	v_lshlrev_b32_e32 v20, 16, v196
	v_mul_f32_e32 v7, 0xbfb8aa3b, v20
	v_exp_f32_e32 v7, v7
	v_and_b32_e32 v21, 0xffff0000, v196
	v_lshlrev_b32_e32 v196, 16, v197
	v_and_b32_e32 v197, 0xffff0000, v197
	v_add_f32_e32 v7, 1.0, v7
	v_rcp_f32_e32 v22, v7
	v_mul_f32_e32 v7, 0xbfb8aa3b, v21
	v_exp_f32_e32 v7, v7
	v_and_b32_e32 v25, 0xffff0000, v164
	v_pk_mul_f32 v[24:25], v[26:27], v[24:25]
	v_add_f32_e32 v7, 1.0, v7
	v_rcp_f32_e32 v23, v7
	v_mul_f32_e32 v7, 0xbfb8aa3b, v196
	v_exp_f32_e32 v7, v7
	v_pk_mul_f32 v[20:21], v[22:23], v[20:21]
	s_nop 0
	v_pk_mul_f32 v[20:21], v[24:25], v[20:21]
	v_add_f32_e32 v7, 1.0, v7
	v_rcp_f32_e32 v164, v7
	v_mul_f32_e32 v7, 0xbfb8aa3b, v197
	v_exp_f32_e32 v7, v7
	v_cvt_pk_bf16_f32 v128, v20, v21
	v_lshlrev_b32_e32 v20, 16, v165
	v_and_b32_e32 v21, 0xffff0000, v165
	v_add_f32_e32 v7, 1.0, v7
	v_rcp_f32_e32 v165, v7
	v_lshlrev_b32_e32 v22, 16, v129
	v_and_b32_e32 v23, 0xffff0000, v129
	v_pk_mul_f32 v[20:21], v[22:23], v[20:21]
	v_pk_mul_f32 v[164:165], v[164:165], v[196:197]
	v_lshlrev_b32_e32 v22, 16, v130
	v_pk_mul_f32 v[164:165], v[20:21], v[164:165]
	v_lshlrev_b32_e32 v20, 16, v166
	v_cvt_pk_bf16_f32 v129, v164, v165
	v_lshlrev_b32_e32 v164, 16, v198
	v_mul_f32_e32 v7, 0xbfb8aa3b, v164
	v_exp_f32_e32 v7, v7
	v_and_b32_e32 v165, 0xffff0000, v198
	v_and_b32_e32 v21, 0xffff0000, v166
	v_and_b32_e32 v23, 0xffff0000, v130
	v_add_f32_e32 v7, 1.0, v7
	v_rcp_f32_e32 v196, v7
	v_mul_f32_e32 v7, 0xbfb8aa3b, v165
	v_exp_f32_e32 v7, v7
	v_pk_mul_f32 v[20:21], v[22:23], v[20:21]
	v_lshlrev_b32_e32 v198, 16, v131
	v_add_f32_e32 v7, 1.0, v7
	v_rcp_f32_e32 v197, v7
	s_nop 0
	v_pk_mul_f32 v[164:165], v[196:197], v[164:165]
	s_nop 0
	v_pk_mul_f32 v[164:165], v[20:21], v[164:165]
	v_lshlrev_b32_e32 v196, 16, v167
	v_cvt_pk_bf16_f32 v130, v164, v165
	v_lshlrev_b32_e32 v164, 16, v199
	v_mul_f32_e32 v7, 0xbfb8aa3b, v164
	v_exp_f32_e32 v7, v7
	v_and_b32_e32 v165, 0xffff0000, v199
	v_and_b32_e32 v197, 0xffff0000, v167
	v_and_b32_e32 v199, 0xffff0000, v131
	v_add_f32_e32 v7, 1.0, v7
	v_rcp_f32_e32 v166, v7
	v_mul_f32_e32 v7, 0xbfb8aa3b, v165
	v_exp_f32_e32 v7, v7
	v_pk_mul_f32 v[196:197], v[198:199], v[196:197]
	v_add_f32_e32 v7, 1.0, v7
	v_rcp_f32_e32 v167, v7
	s_nop 0
	v_pk_mul_f32 v[164:165], v[166:167], v[164:165]
	s_nop 0
	v_pk_mul_f32 v[164:165], v[196:197], v[164:165]
	s_nop 0
	v_cvt_pk_bf16_f32 v131, v164, v165
	global_store_dwordx4 v[4:5], v[128:131], off offset:2048
	v_lshl_add_u64 v[4:5], v[4:5], 0, s[28:29]
	s_waitcnt vmcnt(9)
	v_lshlrev_b32_e32 v26, 16, v132
	v_and_b32_e32 v27, 0xffff0000, v132
	v_lshlrev_b32_e32 v24, 16, v168
	v_lshlrev_b32_e32 v20, 16, v212
	v_mul_f32_e32 v7, 0xbfb8aa3b, v20
	v_exp_f32_e32 v7, v7
	v_and_b32_e32 v21, 0xffff0000, v212
	v_lshlrev_b32_e32 v212, 16, v213
	v_and_b32_e32 v213, 0xffff0000, v213
	v_add_f32_e32 v7, 1.0, v7
	v_rcp_f32_e32 v22, v7
	v_mul_f32_e32 v7, 0xbfb8aa3b, v21
	v_exp_f32_e32 v7, v7
	v_and_b32_e32 v25, 0xffff0000, v168
	v_pk_mul_f32 v[24:25], v[26:27], v[24:25]
	v_add_f32_e32 v7, 1.0, v7
	v_rcp_f32_e32 v23, v7
	v_mul_f32_e32 v7, 0xbfb8aa3b, v212
	v_exp_f32_e32 v7, v7
	v_pk_mul_f32 v[20:21], v[22:23], v[20:21]
	s_nop 0
	v_pk_mul_f32 v[20:21], v[24:25], v[20:21]
	v_add_f32_e32 v7, 1.0, v7
	v_rcp_f32_e32 v168, v7
	v_mul_f32_e32 v7, 0xbfb8aa3b, v213
	v_exp_f32_e32 v7, v7
	v_cvt_pk_bf16_f32 v132, v20, v21
	v_lshlrev_b32_e32 v20, 16, v169
	v_and_b32_e32 v21, 0xffff0000, v169
	v_add_f32_e32 v7, 1.0, v7
	v_rcp_f32_e32 v169, v7
	v_lshlrev_b32_e32 v22, 16, v133
	v_and_b32_e32 v23, 0xffff0000, v133
	v_pk_mul_f32 v[20:21], v[22:23], v[20:21]
	v_pk_mul_f32 v[168:169], v[168:169], v[212:213]
	v_lshlrev_b32_e32 v22, 16, v134
	v_pk_mul_f32 v[168:169], v[20:21], v[168:169]
	v_lshlrev_b32_e32 v20, 16, v170
	v_cvt_pk_bf16_f32 v133, v168, v169
	v_lshlrev_b32_e32 v168, 16, v214
	v_mul_f32_e32 v7, 0xbfb8aa3b, v168
	v_exp_f32_e32 v7, v7
	v_and_b32_e32 v169, 0xffff0000, v214
	v_and_b32_e32 v21, 0xffff0000, v170
	v_and_b32_e32 v23, 0xffff0000, v134
	v_add_f32_e32 v7, 1.0, v7
	v_rcp_f32_e32 v212, v7
	v_mul_f32_e32 v7, 0xbfb8aa3b, v169
	v_exp_f32_e32 v7, v7
	v_pk_mul_f32 v[20:21], v[22:23], v[20:21]
	v_lshlrev_b32_e32 v214, 16, v135
	v_add_f32_e32 v7, 1.0, v7
	v_rcp_f32_e32 v213, v7
	s_nop 0
	v_pk_mul_f32 v[168:169], v[212:213], v[168:169]
	s_nop 0
	v_pk_mul_f32 v[168:169], v[20:21], v[168:169]
	v_lshlrev_b32_e32 v212, 16, v171
	v_cvt_pk_bf16_f32 v134, v168, v169
	v_lshlrev_b32_e32 v168, 16, v215
	v_mul_f32_e32 v7, 0xbfb8aa3b, v168
	v_exp_f32_e32 v7, v7
	v_and_b32_e32 v169, 0xffff0000, v215
	v_and_b32_e32 v213, 0xffff0000, v171
	v_and_b32_e32 v215, 0xffff0000, v135
	v_add_f32_e32 v7, 1.0, v7
	v_rcp_f32_e32 v170, v7
	v_mul_f32_e32 v7, 0xbfb8aa3b, v169
	v_exp_f32_e32 v7, v7
	v_pk_mul_f32 v[212:213], v[214:215], v[212:213]
	v_add_f32_e32 v7, 1.0, v7
	v_rcp_f32_e32 v171, v7
	s_nop 0
	v_pk_mul_f32 v[168:169], v[170:171], v[168:169]
	s_nop 0
	v_pk_mul_f32 v[168:169], v[212:213], v[168:169]
	s_nop 0
	v_cvt_pk_bf16_f32 v135, v168, v169
	global_store_dwordx4 v[4:5], v[132:135], off offset:2048
	v_lshl_add_u64 v[4:5], v[4:5], 0, s[28:29]
	s_waitcnt vmcnt(8)
	v_lshlrev_b32_e32 v26, 16, v136
	v_and_b32_e32 v27, 0xffff0000, v136
	v_lshlrev_b32_e32 v24, 16, v172
	v_lshlrev_b32_e32 v20, 16, v216
	v_mul_f32_e32 v7, 0xbfb8aa3b, v20
	v_exp_f32_e32 v7, v7
	v_and_b32_e32 v21, 0xffff0000, v216
	v_lshlrev_b32_e32 v216, 16, v217
	v_and_b32_e32 v217, 0xffff0000, v217
	v_add_f32_e32 v7, 1.0, v7
	v_rcp_f32_e32 v22, v7
	v_mul_f32_e32 v7, 0xbfb8aa3b, v21
	v_exp_f32_e32 v7, v7
	v_and_b32_e32 v25, 0xffff0000, v172
	v_pk_mul_f32 v[24:25], v[26:27], v[24:25]
	v_add_f32_e32 v7, 1.0, v7
	v_rcp_f32_e32 v23, v7
	v_mul_f32_e32 v7, 0xbfb8aa3b, v216
	v_exp_f32_e32 v7, v7
	v_pk_mul_f32 v[20:21], v[22:23], v[20:21]
	s_nop 0
	v_pk_mul_f32 v[20:21], v[24:25], v[20:21]
	v_add_f32_e32 v7, 1.0, v7
	v_rcp_f32_e32 v172, v7
	v_mul_f32_e32 v7, 0xbfb8aa3b, v217
	v_exp_f32_e32 v7, v7
	v_cvt_pk_bf16_f32 v136, v20, v21
	v_lshlrev_b32_e32 v20, 16, v173
	v_and_b32_e32 v21, 0xffff0000, v173
	v_add_f32_e32 v7, 1.0, v7
	v_rcp_f32_e32 v173, v7
	v_lshlrev_b32_e32 v22, 16, v137
	v_and_b32_e32 v23, 0xffff0000, v137
	v_pk_mul_f32 v[20:21], v[22:23], v[20:21]
	v_pk_mul_f32 v[172:173], v[172:173], v[216:217]
	v_lshlrev_b32_e32 v22, 16, v138
	v_pk_mul_f32 v[172:173], v[20:21], v[172:173]
	v_lshlrev_b32_e32 v20, 16, v174
	v_cvt_pk_bf16_f32 v137, v172, v173
	v_lshlrev_b32_e32 v172, 16, v218
	v_mul_f32_e32 v7, 0xbfb8aa3b, v172
	v_exp_f32_e32 v7, v7
	v_and_b32_e32 v173, 0xffff0000, v218
	v_and_b32_e32 v21, 0xffff0000, v174
	v_and_b32_e32 v23, 0xffff0000, v138
	v_add_f32_e32 v7, 1.0, v7
	v_rcp_f32_e32 v216, v7
	v_mul_f32_e32 v7, 0xbfb8aa3b, v173
	v_exp_f32_e32 v7, v7
	v_pk_mul_f32 v[20:21], v[22:23], v[20:21]
	v_lshlrev_b32_e32 v218, 16, v139
	v_add_f32_e32 v7, 1.0, v7
	v_rcp_f32_e32 v217, v7
	s_nop 0
	v_pk_mul_f32 v[172:173], v[216:217], v[172:173]
	s_nop 0
	v_pk_mul_f32 v[172:173], v[20:21], v[172:173]
	v_lshlrev_b32_e32 v216, 16, v175
	v_cvt_pk_bf16_f32 v138, v172, v173
	v_lshlrev_b32_e32 v172, 16, v219
	v_mul_f32_e32 v7, 0xbfb8aa3b, v172
	v_exp_f32_e32 v7, v7
	v_and_b32_e32 v173, 0xffff0000, v219
	v_and_b32_e32 v217, 0xffff0000, v175
	v_and_b32_e32 v219, 0xffff0000, v139
	v_add_f32_e32 v7, 1.0, v7
	v_rcp_f32_e32 v174, v7
	v_mul_f32_e32 v7, 0xbfb8aa3b, v173
	v_exp_f32_e32 v7, v7
	v_pk_mul_f32 v[216:217], v[218:219], v[216:217]
	v_add_f32_e32 v7, 1.0, v7
	v_rcp_f32_e32 v175, v7
	s_nop 0
	v_pk_mul_f32 v[172:173], v[174:175], v[172:173]
	s_nop 0
	v_pk_mul_f32 v[172:173], v[216:217], v[172:173]
	s_nop 0
	v_cvt_pk_bf16_f32 v139, v172, v173
	global_store_dwordx4 v[4:5], v[136:139], off offset:2048
	v_lshl_add_u64 v[4:5], v[4:5], 0, s[28:29]
	s_waitcnt vmcnt(7)
	v_lshlrev_b32_e32 v26, 16, v140
	v_and_b32_e32 v27, 0xffff0000, v140
	v_lshlrev_b32_e32 v24, 16, v176
	v_lshlrev_b32_e32 v20, 16, v220
	v_mul_f32_e32 v7, 0xbfb8aa3b, v20
	v_exp_f32_e32 v7, v7
	v_and_b32_e32 v21, 0xffff0000, v220
	v_lshlrev_b32_e32 v220, 16, v221
	v_and_b32_e32 v221, 0xffff0000, v221
	v_add_f32_e32 v7, 1.0, v7
	v_rcp_f32_e32 v22, v7
	v_mul_f32_e32 v7, 0xbfb8aa3b, v21
	v_exp_f32_e32 v7, v7
	v_and_b32_e32 v25, 0xffff0000, v176
	v_pk_mul_f32 v[24:25], v[26:27], v[24:25]
	v_add_f32_e32 v7, 1.0, v7
	v_rcp_f32_e32 v23, v7
	v_mul_f32_e32 v7, 0xbfb8aa3b, v220
	v_exp_f32_e32 v7, v7
	v_pk_mul_f32 v[20:21], v[22:23], v[20:21]
	s_nop 0
	v_pk_mul_f32 v[20:21], v[24:25], v[20:21]
	v_add_f32_e32 v7, 1.0, v7
	v_rcp_f32_e32 v176, v7
	v_mul_f32_e32 v7, 0xbfb8aa3b, v221
	v_exp_f32_e32 v7, v7
	v_cvt_pk_bf16_f32 v140, v20, v21
	v_lshlrev_b32_e32 v20, 16, v177
	v_and_b32_e32 v21, 0xffff0000, v177
	v_add_f32_e32 v7, 1.0, v7
	v_rcp_f32_e32 v177, v7
	v_lshlrev_b32_e32 v22, 16, v141
	v_and_b32_e32 v23, 0xffff0000, v141
	v_pk_mul_f32 v[20:21], v[22:23], v[20:21]
	v_pk_mul_f32 v[176:177], v[176:177], v[220:221]
	v_lshlrev_b32_e32 v22, 16, v142
	v_pk_mul_f32 v[176:177], v[20:21], v[176:177]
	v_lshlrev_b32_e32 v20, 16, v178
	v_cvt_pk_bf16_f32 v141, v176, v177
	v_lshlrev_b32_e32 v176, 16, v222
	v_mul_f32_e32 v7, 0xbfb8aa3b, v176
	v_exp_f32_e32 v7, v7
	v_and_b32_e32 v177, 0xffff0000, v222
	v_and_b32_e32 v21, 0xffff0000, v178
	v_and_b32_e32 v23, 0xffff0000, v142
	v_add_f32_e32 v7, 1.0, v7
	v_rcp_f32_e32 v220, v7
	v_mul_f32_e32 v7, 0xbfb8aa3b, v177
	v_exp_f32_e32 v7, v7
	v_pk_mul_f32 v[20:21], v[22:23], v[20:21]
	v_lshlrev_b32_e32 v222, 16, v143
	v_add_f32_e32 v7, 1.0, v7
	v_rcp_f32_e32 v221, v7
	s_nop 0
	v_pk_mul_f32 v[176:177], v[220:221], v[176:177]
	s_nop 0
	v_pk_mul_f32 v[176:177], v[20:21], v[176:177]
	v_lshlrev_b32_e32 v220, 16, v179
	v_cvt_pk_bf16_f32 v142, v176, v177
	v_lshlrev_b32_e32 v176, 16, v223
	v_mul_f32_e32 v7, 0xbfb8aa3b, v176
	v_exp_f32_e32 v7, v7
	v_and_b32_e32 v177, 0xffff0000, v223
	v_and_b32_e32 v221, 0xffff0000, v179
	v_and_b32_e32 v223, 0xffff0000, v143
	v_add_f32_e32 v7, 1.0, v7
	v_rcp_f32_e32 v178, v7
	v_mul_f32_e32 v7, 0xbfb8aa3b, v177
	v_exp_f32_e32 v7, v7
	v_pk_mul_f32 v[220:221], v[222:223], v[220:221]
	v_add_f32_e32 v7, 1.0, v7
	v_rcp_f32_e32 v179, v7
	s_nop 0
	v_pk_mul_f32 v[176:177], v[178:179], v[176:177]
	s_nop 0
	v_pk_mul_f32 v[176:177], v[220:221], v[176:177]
	s_nop 0
	v_cvt_pk_bf16_f32 v143, v176, v177
	global_store_dwordx4 v[4:5], v[140:143], off offset:2048
	s_branch .LBB0_305

.LBB0_502:
	s_or_b64 exec, exec, s[0:1]
	s_mov_b32 s0, 0x80000
	v_cmp_gt_i32_e32 vcc, s0, v164
	s_mov_b64 s[0:1], exec
	s_and_b64 s[18:19], s[0:1], vcc
	v_mov_b32_e32 v234, 1
	v_mov_b64_e32 v[236:237], 0x3bf
	v_mov_b64_e32 v[238:239], 0x3c0
	v_mov_b32_e32 v26, 0xfffff800
	v_mov_b32_e32 v27, 0xffffff00
	v_mov_b32_e32 v235, 0x80
	v_mov_b32_e32 v240, 0xbcb504f3
	v_mov_b32_e32 v241, 0x3cb504f3
	v_mov_b64_e32 v[242:243], 0x17f
	v_mov_b64_e32 v[244:245], 0x180
	s_mov_b64 exec, s[18:19]
	s_cbranch_execz .LBB0_505
	s_mul_i32 s18, s2, 0
	s_mov_b32 s19, 0
	s_cmp_lt_u32 s2, 2
	s_cbranch_scc1 .Ldeal_r_done
	s_cmp_lt_u32 s2, 0x80
	s_cbranch_scc0 .Ldeal_r_hi
	s_sub_i32 s18, s2, 2
	s_mul_i32 s18, s18, 3
	s_add_i32 s18, s18, 0
	s_mov_b32 s19, 3
	s_branch .Ldeal_r_done
.Ldeal_r_hi:
	s_cmp_lt_u32 s2, 0xe0
	s_cbranch_scc1 .Ldeal_r_idle
	s_sub_i32 s18, s2, 0xe0
	s_mul_i32 s18, s18, 0
	s_add_i32 s18, s18, 378
	s_mov_b32 s19, 0
	s_branch .Ldeal_r_done
.Ldeal_r_idle:
	s_sub_i32 s22, s2, 0x80
	s_mul_i32 s18, s22, 6
	s_min_u32 s19, s22, 70
	s_add_i32 s18, s18, s19
	s_add_i32 s18, s18, 378
	s_cmp_lt_u32 s22, 70
	s_cselect_b32 s19, 7, 6

.Ldeal_v_done:
	s_cmp_eq_u32 s1, 0
	s_cbranch_scc1 .LBB0_508
	s_add_i32 s18, s0, s1
	s_mov_b32 s19, s0
.LBB0_507:
	s_mul_hi_u32 s0, s19, 0xaaaaaaab
	s_lshr_b32 s0, s0, 1
	s_mul_i32 s1, s0, 3
	s_sub_i32 s1, s19, s1
	s_cmp_eq_u32 s1, 2
	s_cbranch_scc1 .Lvt_samp
	s_lshl_b32 s0, s0, 1
	s_add_i32 s0, s0, s1
	s_branch .Lvt_have
.Lvt_samp:
	s_addk_i32 s0, 0x400
.Lvt_have:
	s_lshl_b32 s0, s0, 9
	v_add_u32_e32 v164, s0, v205
	v_ashrrev_i32_e32 v20, 6, v164
	v_mov_b64_e32 v[4:5], s[36:37]
	v_and_b32_e32 v21, -8, v20
	v_lshlrev_b32_e32 v0, 1, v2
	v_mad_i64_i32 v[4:5], s[0:1], v21, s77, v[4:5]
	v_lshl_add_u64 v[4:5], v[4:5], 0, v[0:1]
	s_mov_b32 s0, 0xb000
	v_add_co_u32_e64 v8, s[0:1], s0, v4
	v_add_co_u32_e32 v6, vcc, 0x1000, v4
	s_nop 0
	v_addc_co_u32_e64 v9, s[0:1], 0, v5, s[0:1]
	s_mov_b32 s0, 0xd000
	s_nop 0
	v_add_co_u32_e64 v10, s[0:1], s0, v4
	v_addc_co_u32_e32 v7, vcc, 0, v5, vcc
	s_nop 0
	v_addc_co_u32_e64 v11, s[0:1], 0, v5, s[0:1]
	v_add_co_u32_e64 v12, s[0:1], s22, v4
	v_add_co_u32_e32 v16, vcc, 0x3000, v4
	s_nop 0
	v_addc_co_u32_e64 v13, s[0:1], 0, v5, s[0:1]
	s_mov_b32 s0, 0x12000
	s_nop 0
	v_add_co_u32_e64 v14, s[0:1], s0, v4
	v_addc_co_u32_e32 v17, vcc, 0, v5, vcc
	s_nop 0
	v_addc_co_u32_e64 v15, s[0:1], 0, v5, s[0:1]
	v_add_co_u32_e32 v18, vcc, 0x6000, v4
	s_mov_b32 s0, 0x8000
	s_nop 0
	v_addc_co_u32_e32 v19, vcc, 0, v5, vcc
	v_add_co_u32_e32 v4, vcc, s0, v4
	flat_load_ushort v0, v[6:7]
	s_nop 0
	flat_load_ushort v16, v[16:17] offset:2048
	v_addc_co_u32_e32 v5, vcc, 0, v5, vcc
	flat_load_ushort v17, v[18:19]
	s_nop 0
	flat_load_ushort v18, v[4:5] offset:2048
	flat_load_ushort v19, v[8:9]
	s_nop 0
	flat_load_ushort v10, v[10:11] offset:2048
	s_nop 0
	flat_load_ushort v11, v[12:13]
	s_nop 0
	flat_load_ushort v12, v[14:15] offset:2048
	s_add_i32 s19, s19, 1
	s_cmp_ge_u32 s19, s18
	s_cselect_b64 vcc, exec, 0
	v_cmp_gt_i32_e64 s[0:1], s34, v21
	s_or_b64 s[30:31], vcc, s[30:31]
	s_nop 0
	v_cndmask_b32_e64 v4, v26, v27, s[0:1]
	v_and_b32_e32 v4, v4, v20
	v_ashrrev_i32_e32 v5, 31, v4
	v_cndmask_b32_e64 v6, 11, 8, s[0:1]
	v_sub_u32_e32 v8, v21, v4
	v_lshlrev_b64 v[4:5], 10, v[4:5]
	v_lshlrev_b64 v[6:7], v6, v[2:3]
	v_lshl_add_u64 v[4:5], s[24:25], 0, v[4:5]
	v_ashrrev_i32_e32 v9, 31, v8
	v_lshl_add_u64 v[4:5], v[6:7], 1, v[4:5]
	v_lshl_add_u64 v[8:9], v[8:9], 1, v[4:5]
	s_waitcnt vmcnt(0) lgkmcnt(0)
	v_lshl_or_b32 v5, v18, 16, v17
	v_lshl_or_b32 v4, v16, 16, v0
	v_lshl_or_b32 v6, v10, 16, v19
	v_lshl_or_b32 v7, v12, 16, v11
	flat_store_dwordx4 v[8:9], v[4:7]
	s_andn2_b64 exec, exec, s[30:31]
	s_cbranch_execnz .LBB0_507
